# stack: scan nops removed + P2 prologue param touch-prefetch + fox_jlo3 loads de-serialized + P5 wl copy de-serialized + P0 transposes deferred to P1 head
# speedup vs baseline: 1.0111x; 1.0036x over previous
.LBB0_322:
	s_and_b64 vcc, exec, s[12:13]
	s_cbranch_vccz .LBB0_317
	s_and_b64 s[4:5], exec, s[4:5]
	s_cselect_b32 s4, s24, 0
	s_mul_hi_i32 s5, s4, 0x2aaaaaab
	s_lshr_b32 s12, s5, 31
	s_ashr_i32 s5, s5, 4
	s_add_i32 s42, s5, s12
	s_mul_i32 s5, s42, 0x60
	s_sub_i32 s4, s4, s5
	s_ashr_i32 s5, s4, 31
	v_readlane_b32 s52, v233, 2
	s_lshl_b64 s[12:13], s[4:5], 2
	v_readlane_b32 s66, v233, 16
	v_readlane_b32 s67, v233, 17
	s_add_u32 s12, s66, s12
	s_addc_u32 s13, s67, s13
	s_waitcnt lgkmcnt(13)
	global_load_dword v4, v69, s[12:13]
	s_lshl_b32 s24, s4, 6
	s_waitcnt lgkmcnt(12)
	v_or_b32_e32 v0, s24, v65
	v_ashrrev_i32_e32 v1, 31, v0
	v_readlane_b32 s62, v233, 12
	v_readlane_b32 s63, v233, 13
	v_readlane_b32 s64, v233, 14
	v_readlane_b32 s65, v233, 15
	v_lshlrev_b64 v[2:3], 2, v[0:1]
	v_lshl_add_u64 v[0:1], s[62:63], 0, v[2:3]
	v_lshl_add_u64 v[2:3], s[64:65], 0, v[2:3]
	global_load_dword v1, v[0:1], off
	s_andn2_b64 vcc, exec, s[0:1]
	global_load_dword v0, v[2:3], off
	s_mov_b64 s[12:13], -1
	v_readlane_b32 s53, v233, 3
	v_readlane_b32 s54, v233, 4
	v_readlane_b32 s55, v233, 5
	v_readlane_b32 s56, v233, 6
	v_readlane_b32 s57, v233, 7
	v_readlane_b32 s58, v233, 8
	v_readlane_b32 s59, v233, 9
	v_readlane_b32 s60, v233, 10
	v_readlane_b32 s61, v233, 11
	s_waitcnt vmcnt(2)
	v_mul_f32_e32 v2, 0x3fb8aa3b, v4
	v_exp_f32_e32 v2, v2
	s_waitcnt vmcnt(1)
	v_mul_f32_e32 v3, v2, v1
	v_mul_f32_e32 v3, 0x3fb8aa3b, v3
	s_waitcnt vmcnt(0)
	v_mul_f32_e32 v2, v2, v0
	v_mul_f32_e32 v4, 0.15915494, v2
	v_floor_f32_e32 v4, v4
	v_fma_f32 v2, v2, 0.15915494, -v4
	v_exp_f32_e32 v3, v3
	v_cos_f32_e32 v4, v2
	v_sin_f32_e32 v2, v2
	v_mul_f32_e32 v116, v3, v4
	v_mul_f32_e32 v87, v3, v2
	s_cbranch_vccnz .LBB0_327
	v_and_b32_e32 v200, 31, v65
	v_lshlrev_b32_e32 v200, 7, v200
	v_lshl_add_u32 v200, s24, 6, v200
	v_mov_b32_e32 v201, 0
	v_cmp_gt_u32_e32 vcc, 32, v65
	v_readlane_b32 s98, v233, 21
	v_readlane_b32 s99, v233, 22
	v_readlane_b32 s100, v233, 23
	v_readlane_b32 s101, v233, 24
	v_mov_b32_e32 v202, s98
	v_mov_b32_e32 v203, s99
	v_mov_b32_e32 v204, s100
	v_mov_b32_e32 v205, s101
	v_cndmask_b32_e32 v202, v204, v202, vcc
	v_cndmask_b32_e32 v203, v205, v203, vcc
	v_lshl_add_u64 v[202:203], v[202:203], 0, v[200:201]
	global_load_dword v206, v[202:203], off
	v_readlane_b32 s98, v233, 25
	v_readlane_b32 s99, v233, 26
	v_readlane_b32 s100, v233, 27
	v_readlane_b32 s101, v233, 28
	v_mov_b32_e32 v202, s98
	v_mov_b32_e32 v203, s99
	v_mov_b32_e32 v204, s100
	v_mov_b32_e32 v205, s101
	v_cndmask_b32_e32 v202, v204, v202, vcc
	v_cndmask_b32_e32 v203, v205, v203, vcc
	v_lshl_add_u64 v[202:203], v[202:203], 0, v[200:201]
	global_load_dword v206, v[202:203], off
	s_ashr_i32 s43, s42, 31
	v_readlane_b32 s12, v232, 49
	s_lshl_b64 s[26:27], s[42:43], 11
	v_readlane_b32 s13, v232, 50
	v_or_b32_e32 v4, s26, v64
	v_mov_b32_e32 v85, v69
	v_mov_b64_e32 v[2:3], s[12:13]
	v_mad_u64_u32 v[4:5], s[12:13], v4, s19, v[2:3]
	s_lshl_b32 s12, s4, 4
	s_ashr_i32 s13, s12, 31
	v_mad_i32_i24 v5, s27, v112, v5
	s_lshl_b64 s[4:5], s[12:13], 1
	v_lshl_add_u64 v[4:5], v[4:5], 0, s[4:5]
	s_waitcnt lgkmcnt(5)
	v_lshl_add_u64 v[52:53], v[4:5], 0, v[68:69]
	v_or_b32_e32 v4, s26, v66
	v_mad_u64_u32 v[2:3], s[28:29], v4, s19, v[2:3]
	v_mad_i32_i24 v3, s27, v112, v3
	v_lshl_add_u64 v[2:3], v[2:3], 0, s[4:5]
	v_mov_b32_e32 v86, v0
	v_add_f32_e32 v4, -1.0, v116
	v_mov_b32_e32 v5, v1
	v_lshl_add_u64 v[90:91], v[2:3], 0, v[84:85]
	v_pk_mul_f32 v[2:3], v[0:1], v[86:87]
	v_pk_mul_f32 v[6:7], v[0:1], v[4:5]
	v_readlane_b32 s48, v233, 21
	v_add_f32_e32 v5, v2, v7
	v_sub_f32_e32 v2, v3, v6
	v_div_scale_f32 v3, s[26:27], v5, v5, v2
	v_rcp_f32_e32 v6, v3
	v_readlane_b32 s56, v233, 29
	v_readlane_b32 s57, v233, 30
	s_mov_b32 s13, 0
	v_fma_f32 v7, -v3, v6, 1.0
	v_fmac_f32_e32 v6, v7, v6
	v_div_scale_f32 v7, vcc, v2, v5, v2
	v_mul_f32_e32 v8, v7, v6
	v_fma_f32 v9, -v3, v8, v7
	v_fmac_f32_e32 v8, v9, v6
	v_fma_f32 v3, -v3, v8, v7
	v_div_fmas_f32 v3, v3, v6, v8
	s_waitcnt lgkmcnt(3)
	v_div_fixup_f32 v24, v3, v5, v2
	v_mov_b32_e32 v2, v87
	v_mov_b32_e32 v3, v4
	v_pk_mul_f32 v[0:1], v[0:1], v[2:3]
	v_readlane_b32 s49, v233, 22
	v_add_f32_e32 v0, v0, v1
	v_div_scale_f32 v1, s[26:27], v5, v5, v0
	v_rcp_f32_e32 v2, v1
	v_readlane_b32 s50, v233, 23
	v_readlane_b32 s51, v233, 24
	v_readlane_b32 s52, v233, 25
	v_fma_f32 v3, -v1, v2, 1.0
	v_fmac_f32_e32 v2, v3, v2
	v_div_scale_f32 v3, vcc, v0, v5, v0
	v_mul_f32_e32 v4, v3, v2
	v_fma_f32 v6, -v1, v4, v3
	v_fmac_f32_e32 v4, v6, v2
	v_fma_f32 v1, -v1, v4, v3
	v_div_fmas_f32 v1, v1, v2, v4
	v_or_b32_e32 v4, s24, v64
	v_div_fixup_f32 v1, v1, v5, v0
	v_ashrrev_i32_e32 v5, 31, v4
	v_lshlrev_b64 v[8:9], 6, v[4:5]
	v_lshl_add_u64 v[10:11], v[72:73], 0, v[8:9]
	v_lshl_add_u64 v[8:9], v[74:75], 0, v[8:9]
	global_load_dwordx4 v[4:7], v[10:11], off
	global_load_dwordx4 v[12:15], v[10:11], off offset:16
	global_load_dwordx4 v[16:19], v[8:9], off
	global_load_dwordx4 v[20:23], v[8:9], off offset:16
	ds_bpermute_b32 v0, v113, v24
	ds_bpermute_b32 v2, v113, v1
	v_readlane_b32 s53, v233, 26
	v_readlane_b32 s54, v233, 27
	v_readlane_b32 s55, v233, 28
	v_readlane_b32 s58, v233, 31
	v_readlane_b32 s59, v233, 32
	v_readlane_b32 s60, v233, 33
	v_readlane_b32 s61, v233, 34
	v_readlane_b32 s62, v233, 35
	v_readlane_b32 s63, v233, 36
	s_waitcnt vmcnt(1) lgkmcnt(1)
	v_pk_mul_f32 v[16:17], v[0:1], v[16:17] op_sel_hi:[0,1]
	s_waitcnt vmcnt(0)
	v_pk_mul_f32 v[20:21], v[20:21], v[0:1] op_sel_hi:[1,0]
	v_pk_mul_f32 v[18:19], v[0:1], v[18:19] op_sel_hi:[0,1]
	s_waitcnt lgkmcnt(0)
	v_pk_fma_f32 v[12:13], v[12:13], v[2:3], v[20:21] op_sel_hi:[1,0,1] neg_lo:[0,0,1] neg_hi:[0,0,1]
	v_pk_mul_f32 v[22:23], v[22:23], v[0:1] op_sel_hi:[1,0]
	v_pk_fma_f32 v[6:7], v[2:3], v[6:7], v[18:19] op_sel_hi:[0,1,1] neg_lo:[0,0,1] neg_hi:[0,0,1]
	v_pk_fma_f32 v[4:5], v[2:3], v[4:5], v[16:17] op_sel_hi:[0,1,1] neg_lo:[0,0,1] neg_hi:[0,0,1]
	v_cvt_pk_bf16_f32 v28, v4, v5
	v_cvt_pk_bf16_f32 v29, v6, v7
	v_cvt_pk_bf16_f32 v30, v12, v13
	v_or_b32_e32 v12, s24, v67
	v_pk_fma_f32 v[14:15], v[14:15], v[2:3], v[22:23] op_sel_hi:[1,0,1] neg_lo:[0,0,1] neg_hi:[0,0,1]
	v_ashrrev_i32_e32 v13, 31, v12
	v_cvt_pk_bf16_f32 v31, v14, v15
	v_lshlrev_b64 v[14:15], 6, v[12:13]
	v_lshl_add_u64 v[12:13], v[72:73], 0, v[14:15]
	v_lshl_add_u64 v[14:15], v[74:75], 0, v[14:15]
	ds_bpermute_b32 v4, v114, v24
	global_load_dwordx4 v[16:19], v[12:13], off
	global_load_dwordx4 v[20:23], v[12:13], off offset:16
	global_load_dwordx4 v[24:27], v[14:15], off
	global_load_dwordx4 v[32:35], v[14:15], off offset:16
	ds_bpermute_b32 v6, v114, v1
	s_waitcnt vmcnt(1) lgkmcnt(1)
	v_pk_mul_f32 v[24:25], v[4:5], v[24:25] op_sel_hi:[0,1]
	s_waitcnt vmcnt(0)
	v_pk_mul_f32 v[32:33], v[32:33], v[4:5] op_sel_hi:[1,0]
	v_pk_mul_f32 v[34:35], v[34:35], v[4:5] op_sel_hi:[1,0]
	v_pk_mul_f32 v[26:27], v[4:5], v[26:27] op_sel_hi:[0,1]
	s_waitcnt lgkmcnt(0)
	v_pk_fma_f32 v[22:23], v[22:23], v[6:7], v[34:35] op_sel_hi:[1,0,1] neg_lo:[0,0,1] neg_hi:[0,0,1]
	v_pk_fma_f32 v[20:21], v[20:21], v[6:7], v[32:33] op_sel_hi:[1,0,1] neg_lo:[0,0,1] neg_hi:[0,0,1]
	v_pk_fma_f32 v[18:19], v[6:7], v[18:19], v[26:27] op_sel_hi:[0,1,1] neg_lo:[0,0,1] neg_hi:[0,0,1]
	v_pk_fma_f32 v[16:17], v[6:7], v[16:17], v[24:25] op_sel_hi:[0,1,1] neg_lo:[0,0,1] neg_hi:[0,0,1]
	v_cvt_pk_bf16_f32 v40, v16, v17
	v_cvt_pk_bf16_f32 v41, v18, v19
	v_cvt_pk_bf16_f32 v42, v20, v21
	v_cvt_pk_bf16_f32 v43, v22, v23
	global_load_dwordx4 v[16:19], v[10:11], off
	global_load_dwordx4 v[20:23], v[10:11], off offset:16
	global_load_dwordx4 v[24:27], v[8:9], off
	s_nop 0
	global_load_dwordx4 v[8:11], v[8:9], off offset:16
	s_waitcnt vmcnt(0)
	v_pk_mul_f32 v[8:9], v[2:3], v[8:9] op_sel_hi:[0,1]
	v_pk_mul_f32 v[10:11], v[2:3], v[10:11] op_sel_hi:[0,1]
	v_pk_fma_f32 v[8:9], v[0:1], v[20:21], v[8:9] op_sel_hi:[0,1,1]
	v_pk_mul_f32 v[20:21], v[2:3], v[24:25] op_sel_hi:[0,1]
	v_pk_mul_f32 v[2:3], v[2:3], v[26:27] op_sel_hi:[0,1]
	v_pk_fma_f32 v[10:11], v[0:1], v[22:23], v[10:11] op_sel_hi:[0,1,1]
	v_pk_fma_f32 v[2:3], v[0:1], v[18:19], v[2:3] op_sel_hi:[0,1,1]
	v_pk_fma_f32 v[0:1], v[0:1], v[16:17], v[20:21] op_sel_hi:[0,1,1]
	v_cvt_pk_bf16_f32 v44, v0, v1
	v_cvt_pk_bf16_f32 v45, v2, v3
	v_cvt_pk_bf16_f32 v46, v8, v9
	v_cvt_pk_bf16_f32 v47, v10, v11
	global_load_dwordx4 v[0:3], v[12:13], off
	global_load_dwordx4 v[8:11], v[12:13], off offset:16
	global_load_dwordx4 v[16:19], v[14:15], off
	s_nop 0
	global_load_dwordx4 v[12:15], v[14:15], off offset:16
	s_waitcnt vmcnt(0)
	v_pk_mul_f32 v[12:13], v[6:7], v[12:13] op_sel_hi:[0,1]
	v_pk_fma_f32 v[8:9], v[4:5], v[8:9], v[12:13] op_sel_hi:[0,1,1]
	v_pk_mul_f32 v[12:13], v[6:7], v[16:17] op_sel_hi:[0,1]
	v_pk_fma_f32 v[0:1], v[4:5], v[0:1], v[12:13] op_sel_hi:[0,1,1]
	v_cvt_pk_bf16_f32 v48, v0, v1
	v_or_b32_e32 v0, s12, v66
	v_pk_mul_f32 v[14:15], v[6:7], v[14:15] op_sel_hi:[0,1]
	v_pk_mul_f32 v[6:7], v[6:7], v[18:19] op_sel_hi:[0,1]
	v_ashrrev_i32_e32 v1, 31, v0
	v_pk_fma_f32 v[10:11], v[4:5], v[10:11], v[14:15] op_sel_hi:[0,1,1]
	v_pk_fma_f32 v[2:3], v[4:5], v[2:3], v[6:7] op_sel_hi:[0,1,1]
	v_lshlrev_b64 v[4:5], 8, v[0:1]
	v_cvt_pk_bf16_f32 v49, v2, v3
	v_cvt_pk_bf16_f32 v50, v8, v9
	v_cvt_pk_bf16_f32 v51, v10, v11
	v_lshl_add_u64 v[10:11], v[78:79], 0, v[4:5]
	v_lshl_add_u64 v[8:9], v[76:77], 0, v[4:5]
	global_load_dwordx4 v[4:7], v[10:11], off
	global_load_dwordx4 v[0:3], v[8:9], off
	s_waitcnt vmcnt(1)
	v_xor_b32_e32 v4, 0x80000000, v4
	s_waitcnt vmcnt(0)
	v_cvt_pk_bf16_f32 v16, v0, v4
	v_xor_b32_e32 v0, 0x80000000, v5
	v_cvt_pk_bf16_f32 v17, v1, v0
	v_xor_b32_e32 v0, 0x80000000, v6
	v_cvt_pk_bf16_f32 v18, v2, v0
	v_xor_b32_e32 v0, 0x80000000, v7
	v_cvt_pk_bf16_f32 v19, v3, v0
	global_load_dwordx4 v[0:3], v[8:9], off offset:64
	global_load_dwordx4 v[4:7], v[10:11], off offset:64
	s_waitcnt vmcnt(0)
	v_xor_b32_e32 v4, 0x80000000, v4
	v_cvt_pk_bf16_f32 v20, v0, v4
	v_xor_b32_e32 v0, 0x80000000, v5
	v_cvt_pk_bf16_f32 v21, v1, v0
	v_xor_b32_e32 v0, 0x80000000, v6
	v_cvt_pk_bf16_f32 v22, v2, v0
	v_xor_b32_e32 v0, 0x80000000, v7
	v_cvt_pk_bf16_f32 v23, v3, v0
	global_load_dwordx4 v[0:3], v[8:9], off offset:128
	global_load_dwordx4 v[4:7], v[10:11], off offset:128
	s_waitcnt vmcnt(0)
	v_xor_b32_e32 v4, 0x80000000, v4
	v_cvt_pk_bf16_f32 v24, v0, v4
	v_xor_b32_e32 v0, 0x80000000, v5
	v_cvt_pk_bf16_f32 v25, v1, v0
	v_xor_b32_e32 v0, 0x80000000, v6
	v_cvt_pk_bf16_f32 v26, v2, v0
	v_xor_b32_e32 v0, 0x80000000, v7
	v_cvt_pk_bf16_f32 v27, v3, v0
	global_load_dwordx4 v[0:3], v[8:9], off offset:192
	global_load_dwordx4 v[4:7], v[10:11], off offset:192
	s_waitcnt vmcnt(0)
	v_xor_b32_e32 v4, 0x80000000, v4
	v_cvt_pk_bf16_f32 v32, v0, v4
	v_xor_b32_e32 v0, 0x80000000, v5
	v_cvt_pk_bf16_f32 v33, v1, v0
	v_xor_b32_e32 v0, 0x80000000, v6
	v_cvt_pk_bf16_f32 v34, v2, v0
	v_xor_b32_e32 v0, 0x80000000, v7
	v_cvt_pk_bf16_f32 v35, v3, v0
	v_or_b32_e32 v0, s12, v70
	v_ashrrev_i32_e32 v1, 31, v0
	v_lshl_add_u64 v[0:1], v[0:1], 2, s[56:57]
	global_load_dwordx4 v[36:39], v[0:1], off
	global_load_dwordx4 v[54:57], v[52:53], off
	s_waitcnt vmcnt(0)
	v_mfma_f32_32x32x16_bf16 v[0:15], v[54:57], v[28:31], 0
	s_nop 11
	ds_write_b128 v71, v[0:3]
	ds_write_b128 v71, v[4:7] offset:32
	ds_write_b128 v71, v[8:11] offset:64
	ds_write_b128 v71, v[12:15] offset:96
	v_mfma_f32_32x32x16_bf16 v[0:15], v[54:57], v[40:43], 0
	s_nop 11
	ds_write_b128 v71, v[0:3] offset:4608
	ds_write_b128 v71, v[4:7] offset:4640
	ds_write_b128 v71, v[8:11] offset:4672
	ds_write_b128 v71, v[12:15] offset:4704
	v_mfma_f32_32x32x16_bf16 v[0:15], v[54:57], v[44:47], 0
	s_nop 11
	ds_write_b128 v71, v[0:3] offset:9216
	ds_write_b128 v71, v[4:7] offset:9248
	ds_write_b128 v71, v[8:11] offset:9280
	ds_write_b128 v71, v[12:15] offset:9312
	v_mfma_f32_32x32x16_bf16 v[0:15], v[54:57], v[48:51], 0
	s_nop 11
	ds_write_b128 v71, v[0:3] offset:13824
	ds_write_b128 v71, v[4:7] offset:13856
	ds_write_b128 v71, v[8:11] offset:13888
	ds_write_b128 v71, v[12:15] offset:13920
	v_add_co_u32_e32 v0, vcc, s20, v52
	s_mov_b32 s12, 0xc000
	s_nop 0
	v_addc_co_u32_e32 v1, vcc, 0, v53, vcc
	global_load_dwordx4 v[60:63], v[0:1], off
	v_add_co_u32_e32 v0, vcc, s21, v52
	s_nop 1
	v_addc_co_u32_e32 v1, vcc, 0, v53, vcc
	global_load_dwordx4 v[56:59], v[0:1], off
	global_load_dwordx2 v[92:93], v[90:91], off
	v_add_co_u32_e32 v0, vcc, s12, v90
	s_mov_b32 s12, 0x48000
	s_nop 0
	v_addc_co_u32_e32 v1, vcc, 0, v91, vcc
	global_load_dwordx2 v[100:101], v[0:1], off
	s_waitcnt lgkmcnt(0)
	s_barrier
	v_add_co_u32_e32 v0, vcc, s12, v52
	s_waitcnt lgkmcnt(0)
	s_barrier
	s_mov_b32 s12, 0x24000
	s_nop 0
	v_addc_co_u32_e32 v1, vcc, 0, v53, vcc
	global_load_dwordx4 v[52:55], v[0:1], off
	v_add_co_u32_e32 v0, vcc, s20, v90
	s_nop 1
	v_addc_co_u32_e32 v1, vcc, 0, v91, vcc
	global_load_dwordx2 v[88:89], v[0:1], off
	v_add_co_u32_e32 v0, vcc, s12, v90
	s_nop 1
	v_addc_co_u32_e32 v1, vcc, 0, v91, vcc
	global_load_dwordx2 v[90:91], v[0:1], off
	s_waitcnt vmcnt(6)
	v_mfma_f32_32x32x16_bf16 v[0:15], v[60:63], v[28:31], 0
	s_nop 11
	ds_write_b128 v71, v[0:3]
	ds_write_b128 v71, v[4:7] offset:32
	ds_write_b128 v71, v[8:11] offset:64
	ds_write_b128 v71, v[12:15] offset:96
	v_mfma_f32_32x32x16_bf16 v[0:15], v[60:63], v[40:43], 0
	s_nop 11
	ds_write_b128 v71, v[0:3] offset:4608
	ds_write_b128 v71, v[4:7] offset:4640
	ds_write_b128 v71, v[8:11] offset:4672
	ds_write_b128 v71, v[12:15] offset:4704
	v_mfma_f32_32x32x16_bf16 v[0:15], v[60:63], v[44:47], 0
	s_nop 11
	ds_write_b128 v71, v[0:3] offset:9216
	ds_write_b128 v71, v[4:7] offset:9248
	ds_write_b128 v71, v[8:11] offset:9280
	ds_write_b128 v71, v[12:15] offset:9312
	v_mfma_f32_32x32x16_bf16 v[0:15], v[60:63], v[48:51], 0
	s_nop 11
	ds_write_b128 v71, v[0:3] offset:13824
	ds_write_b128 v71, v[4:7] offset:13856
	ds_write_b128 v71, v[8:11] offset:13888
	ds_write_b128 v71, v[12:15] offset:13920
	v_mad_i64_i32 v[94:95], s[24:25], s42, v115, v[80:81]
	v_mad_i64_i32 v[96:97], s[24:25], s42, v115, v[82:83]
	s_mov_b32 s12, -2

.LBB0_717:
	s_or_b64 exec, exec, s[0:1]
	s_waitcnt lgkmcnt(0)
	v_mov_b32_e32 v0, v210
	s_movk_i32 s0, 0x1800
	s_barrier
	s_nop 0
	v_readfirstlane_b32 s14, v0
	v_cmp_gt_i32_e32 vcc, s0, v0
	s_and_saveexec_b64 s[0:1], vcc
	s_cbranch_execz .LBB0_720
	v_ashrrev_i32_e32 v1, 31, v0
	v_lshl_add_u64 v[2:3], v[0:1], 4, s[92:93]
	s_mov_b64 s[4:5], 0x1f0000
	v_lshl_add_u64 v[2:3], v[2:3], 0, s[4:5]
	v_lshl_add_u32 v1, v0, 4, 0
	s_mov_b64 s[24:25], 0x2000
	global_load_dwordx4 v[100:103], v[2:3], off
	v_lshl_add_u64 v[2:3], v[2:3], 0, s[24:25]
	global_load_dwordx4 v[104:107], v[2:3], off
	v_lshl_add_u64 v[2:3], v[2:3], 0, s[24:25]
	global_load_dwordx4 v[108:111], v[2:3], off
	v_lshl_add_u64 v[2:3], v[2:3], 0, s[24:25]
	global_load_dwordx4 v[112:115], v[2:3], off
	v_lshl_add_u64 v[2:3], v[2:3], 0, s[24:25]
	global_load_dwordx4 v[116:119], v[2:3], off
	v_lshl_add_u64 v[2:3], v[2:3], 0, s[24:25]
	global_load_dwordx4 v[120:123], v[2:3], off
	v_lshl_add_u64 v[2:3], v[2:3], 0, s[24:25]
	global_load_dwordx4 v[124:127], v[2:3], off
	v_lshl_add_u64 v[2:3], v[2:3], 0, s[24:25]
	global_load_dwordx4 v[128:131], v[2:3], off
	v_lshl_add_u64 v[2:3], v[2:3], 0, s[24:25]
	global_load_dwordx4 v[132:135], v[2:3], off
	v_lshl_add_u64 v[2:3], v[2:3], 0, s[24:25]
	global_load_dwordx4 v[136:139], v[2:3], off
	v_lshl_add_u64 v[2:3], v[2:3], 0, s[24:25]
	global_load_dwordx4 v[140:143], v[2:3], off
	v_lshl_add_u64 v[2:3], v[2:3], 0, s[24:25]
	global_load_dwordx4 v[144:147], v[2:3], off
	s_waitcnt vmcnt(0)
	ds_write_b128 v1, v[100:103]
	ds_write_b128 v1, v[104:107] offset:8192
	ds_write_b128 v1, v[108:111] offset:16384
	ds_write_b128 v1, v[112:115] offset:24576
	ds_write_b128 v1, v[116:119] offset:32768
	ds_write_b128 v1, v[120:123] offset:40960
	ds_write_b128 v1, v[124:127] offset:49152
	ds_write_b128 v1, v[128:131] offset:57344
	v_add_u32_e32 v4, 0x10000, v1
	ds_write_b128 v4, v[132:135]
	ds_write_b128 v4, v[136:139] offset:8192
	ds_write_b128 v4, v[140:143] offset:16384
	ds_write_b128 v4, v[144:147] offset:24576
